# exchange: waves 0 and 1 each poll 128 rows of the panel (one poll loop each instead of two sequential halves on wave 0)
# baseline (speedup 1.0000x reference)
;     __device__ __forceinline__ void run(const f32x4 (&v)[2][2][4][2], const Unit& u, int wr, int wc, int fr, int fq, PG8_LAS unsigned char* lds, int wid, int lane) const {
;     ...
;         const int row = wid * 32 + (lane & 31);
;         if (lane < 32) {
;             const float tot = (P[row * 4 + 0] + P[row * 4 + 1]) + (P[row * 4 + 2] + P[row * 4 + 3]);
;             __hip_atomic_store(xbuf + ((size_t)(pmg * BM + row) * 4 + u.pn), tot, __ATOMIC_RELAXED, __HIP_MEMORY_SCOPE_AGENT);
;         }
;         asm volatile("s_waitcnt vmcnt(0)" ::: "memory");
;         if (lane == 0) __hip_atomic_fetch_add(cnt + 64 * pmg, 1u, __ATOMIC_RELAXED, __HIP_MEMORY_SCOPE_AGENT);
;         if (wid == 0) {
;             unsigned sp = 0;
;             while ((unsigned)__builtin_amdgcn_readfirstlane(__hip_atomic_load(cnt + 64 * pmg, __ATOMIC_RELAXED, __HIP_MEMORY_SCOPE_AGENT)) < 32u) { __builtin_amdgcn_s_sleep(2); if (++sp > (1u << 22)) break; }
;             __builtin_amdgcn_fence(__ATOMIC_ACQUIRE, "agent");
;         }
;         asm volatile("s_waitcnt vmcnt(0) lgkmcnt(0)" ::: "memory"); __builtin_amdgcn_s_barrier(); asm volatile("" ::: "memory");
;         if (lane < 32) {
;             const float* slot = xbuf + (size_t)(pmg * BM + row) * 4; float t = 0.f;
; #pragma unroll
;             for (int k = 0; k < 4; ++k) t += __hip_atomic_load(slot + k, __ATOMIC_RELAXED, __HIP_MEMORY_SCOPE_AGENT);
;             S[row] = rsqrtf(t * (1.0f / 1024.0f) + eps);
;     __device__ __forceinline__ void fused(f32x4 (&acc)[2][2][4][2], const Unit& u, int wr, int wc, int fr, int fq, PG8_LAS unsigned char* lds, int wid, int lane) const {
;     ...
;         {
;             f32x4 g[2][2];
; #pragma unroll
;             for (int bj = 0; bj < 2; ++bj)
; #pragma unroll
;                 for (int n = 0; n < 2; ++n) g[bj][n] = *(const f32x4*)(gv1 + col0 + bj * HALF + n * 16);
; #pragma unroll
;             for (int ai = 0; ai < 2; ++ai)
; #pragma unroll
;                 for (int m = 0; m < 4; ++m) { const int r = ai * HALF + wr * 64 + m * 16 + fr; const float rs = S[r]; const size_t off = (size_t)(row_off + u.pm * BM + r) * DM + col0;
; #pragma unroll
;                     for (int bj = 0; bj < 2; ++bj)
; #pragma unroll
.LBB0_775:
	s_or_b64 exec, exec, s[10:11]
	v_lshl_add_u32 v152, v129, 2, 0
	s_mov_b64 s[54:55], exec
	s_cmp_lt_u32 s36, 64
	s_cselect_b64 s[50:51], -1, 0
	s_cmp_gt_u32 s36, 127
	s_cbranch_scc1 .LBB0_790
	s_lshl_b32 s26, s59, 8
	s_add_u32 s26, s26, s36
	v_add_u32_e32 v204, s26, v195
	v_ashrrev_i32_e32 v205, 31, v204
	v_lshl_add_u64 v[204:205], v[204:205], 4, s[52:53]
	v_add_u32_e32 v206, s36, v195
	v_lshlrev_b32_e32 v206, 2, v206
	s_mov_b32 s26, 0x40000
.Lpss_a_poll:
	global_load_dwordx4 v[128:131], v[204:205], off sc1
	global_load_dwordx4 v[132:135], v[204:205], off offset:1024 sc1
	s_waitcnt vmcnt(0)
	v_min3_f32 v207, v128, v129, v130
	v_min3_f32 v207, v207, v131, v132
	v_min3_f32 v207, v207, v133, v134
	v_min_f32_e32 v207, v207, v135
	v_cmp_gt_f32_e32 vcc, 0, v207
	s_cbranch_vccz .Lpss_a_ok
	s_sub_u32 s26, s26, 1
	s_cmp_lg_u32 s26, 0
	s_cbranch_scc1 .Lpss_a_poll
.Lpss_a_ok:
	v_add_f32_e32 v128, 0, v128
	v_add_f32_e32 v128, v128, v129
	v_add_f32_e32 v128, v128, v130
	v_add_f32_e32 v128, v128, v131
	v_fmamk_f32 v128, v128, 0x3a800000, v184
	v_mul_f32_e32 v129, 0x4b800000, v128
	v_cmp_gt_f32_e32 vcc, s67, v128
	s_nop 1
	v_cndmask_b32_e32 v128, v128, v129, vcc
	v_rsq_f32_e32 v128, v128
	s_nop 0
	v_mul_f32_e32 v129, 0x45800000, v128
	v_cndmask_b32_e32 v128, v128, v129, vcc
	ds_write_b32 v206, v128 offset:4096
	v_add_f32_e32 v132, 0, v132
	v_add_f32_e32 v132, v132, v133
	v_add_f32_e32 v132, v132, v134
	v_add_f32_e32 v132, v132, v135
	v_fmamk_f32 v132, v132, 0x3a800000, v184
	v_mul_f32_e32 v133, 0x4b800000, v132
	v_cmp_gt_f32_e32 vcc, s67, v132
	s_nop 1
	v_cndmask_b32_e32 v132, v132, v133, vcc
	v_rsq_f32_e32 v132, v132
	s_nop 0
	v_mul_f32_e32 v133, 0x45800000, v132
	v_cndmask_b32_e32 v132, v132, v133, vcc
	ds_write_b32 v206, v132 offset:4352
.LBB0_790:
	s_or_b64 exec, exec, s[54:55]
	s_lshl_b32 s26, s33, 5
	s_lshl_b32 s27, s46, 8
	s_or_b32 s26, s27, s26
	v_lshrrev_b32_e32 v128, 2, v138
	v_and_or_b32 v166, v128, 12, s26
	s_lshl_b32 s26, s18, 12
	s_add_i32 s52, s19, s26
	s_ashr_i32 s53, s52, 31
	s_lshl_b64 s[52:53], s[52:53], 2
	s_add_u32 s19, s14, s52
	s_addc_u32 s26, s15, s53
	s_add_u32 s52, s19, 0x1c0000
	s_addc_u32 s53, s26, 0
	s_lshl_b32 s18, s18, 14
	s_lshl_b32 s19, s37, 8
	s_add_i32 s19, s19, s18
	v_add_u32_e32 v178, s19, v149
	v_ashrrev_i32_e32 v179, 31, v178
	v_ashrrev_i32_e32 v167, 31, v166
	v_lshlrev_b64 v[128:129], 12, v[178:179]
	v_lshlrev_b64 v[146:147], 2, v[166:167]
	v_lshl_add_u64 v[128:129], s[48:49], 0, v[128:129]
	s_waitcnt lgkmcnt(0)
	s_barrier
	v_lshl_add_u64 v[136:137], s[52:53], 0, v[146:147]
	v_lshl_add_u64 v[158:159], v[128:129], 0, v[146:147]
	global_load_dwordx4 v[154:157], v[158:159], off nt
	global_load_dwordx4 v[132:135], v[136:137], off
	s_waitcnt lgkmcnt(0)
	global_load_dwordx4 v[128:131], v[136:137], off offset:64
	global_load_dwordx4 v[168:171], v[158:159], off offset:64 nt
	global_load_dwordx4 v[172:175], v[158:159], off offset:512 nt
	global_load_dwordx4 v[140:143], v[136:137], off offset:512
	s_nop 0
	global_load_dwordx4 v[136:139], v[136:137], off offset:576
	s_nop 0
	global_load_dwordx4 v[180:183], v[158:159], off offset:576 nt
	v_lshl_add_u32 v160, v149, 2, 0
	ds_read_b32 v158, v160 offset:4096
	v_add_u32_e32 v176, 16, v178
	v_ashrrev_i32_e32 v177, 31, v176
	s_waitcnt lgkmcnt(0)
	v_pk_mul_f32 v[124:125], v[124:125], v[158:159] op_sel_hi:[1,0]
	v_pk_mul_f32 v[126:127], v[126:127], v[158:159] op_sel_hi:[1,0]
	v_pk_mul_f32 v[120:121], v[120:121], v[158:159] op_sel_hi:[1,0]
	v_pk_mul_f32 v[122:123], v[122:123], v[158:159] op_sel_hi:[1,0]
	v_pk_mul_f32 v[116:117], v[116:117], v[158:159] op_sel_hi:[1,0]
	v_pk_mul_f32 v[118:119], v[118:119], v[158:159] op_sel_hi:[1,0]
	v_pk_mul_f32 v[112:113], v[112:113], v[158:159] op_sel_hi:[1,0]
	v_pk_mul_f32 v[114:115], v[114:115], v[158:159] op_sel_hi:[1,0]
	v_lshlrev_b64 v[158:159], 12, v[176:177]
	v_lshl_add_u64 v[158:159], s[48:49], 0, v[158:159]
	v_lshl_add_u64 v[158:159], v[158:159], 0, v[146:147]
	s_waitcnt vmcnt(0)
	v_pk_fma_f32 v[126:127], v[134:135], v[126:127], v[156:157]
	v_pk_fma_f32 v[124:125], v[132:133], v[124:125], v[154:155]
	v_pk_fma_f32 v[122:123], v[130:131], v[122:123], v[170:171]
	v_pk_fma_f32 v[120:121], v[128:129], v[120:121], v[168:169]
	v_pk_fma_f32 v[118:119], v[142:143], v[118:119], v[174:175]
	v_pk_fma_f32 v[116:117], v[140:141], v[116:117], v[172:173]
	v_pk_fma_f32 v[114:115], v[138:139], v[114:115], v[182:183]
	v_pk_fma_f32 v[112:113], v[136:137], v[112:113], v[180:181]
	v_add_u32_e32 v168, 32, v178
	global_load_dwordx4 v[154:157], v[158:159], off nt
	global_load_dwordx4 v[170:173], v[158:159], off offset:64 nt
	global_load_dwordx4 v[180:183], v[158:159], off offset:512 nt
	global_load_dwordx4 v[188:191], v[158:159], off offset:576 nt
	ds_read_b32 v158, v160 offset:4160
	v_ashrrev_i32_e32 v169, 31, v168
	v_lshlrev_b64 v[174:175], 12, v[168:169]
	v_lshl_add_u64 v[174:175], s[48:49], 0, v[174:175]
	v_lshl_add_u64 v[192:193], v[174:175], 0, v[146:147]
	s_waitcnt lgkmcnt(0)
	v_pk_mul_f32 v[108:109], v[108:109], v[158:159] op_sel_hi:[1,0]
	v_pk_mul_f32 v[110:111], v[110:111], v[158:159] op_sel_hi:[1,0]
	v_pk_mul_f32 v[104:105], v[104:105], v[158:159] op_sel_hi:[1,0]
	v_pk_mul_f32 v[106:107], v[106:107], v[158:159] op_sel_hi:[1,0]
	v_pk_mul_f32 v[100:101], v[100:101], v[158:159] op_sel_hi:[1,0]
	v_pk_mul_f32 v[102:103], v[102:103], v[158:159] op_sel_hi:[1,0]
	v_pk_mul_f32 v[96:97], v[96:97], v[158:159] op_sel_hi:[1,0]
	v_pk_mul_f32 v[98:99], v[98:99], v[158:159] op_sel_hi:[1,0]
	v_mul_f32_e32 v145, v125, v125
	v_mul_f32_e32 v149, v123, v123
	v_fmac_f32_e32 v145, v124, v124
	v_fmac_f32_e32 v149, v122, v122
	v_mul_f32_e32 v187, v113, v113
	v_fmac_f32_e32 v187, v112, v112
	s_waitcnt vmcnt(3)
;     __device__ __forceinline__ void fused(f32x4 (&acc)[2][2][4][2], const Unit& u, int wr, int wc, int fr, int fq, PG8_LAS unsigned char* lds, int wid, int lane) const {
;     ...
; #pragma unroll
;             for (int ai = 0; ai < 2; ++ai)
; #pragma unroll
;                 for (int m = 0; m < 4; ++m) { const int r = ai * HALF + wr * 64 + m * 16 + fr; const float rs = S[r]; const size_t off = (size_t)(row_off + u.pm * BM + r) * DM + col0;
; #pragma unroll
;                     for (int bj = 0; bj < 2; ++bj)
; #pragma unroll
;                         for (int n = 0; n < 2; ++n) { const f32x4 bs = __builtin_nontemporal_load((const f32x4*)(base + off + bj * HALF + n * 16)); acc[ai][bj][m][n] = bs + acc[ai][bj][m][n] * rs * g[bj][n]; }
;                     asm volatile("" : "+v"(acc[ai][0][m][0]), "+v"(acc[ai][0][m][1]), "+v"(acc[ai][1][m][0]), "+v"(acc[ai][1][m][1]));
;                     if (m & 1) asm volatile("" ::: "memory"); }
	v_pk_fma_f32 v[110:111], v[134:135], v[110:111], v[156:157]
	v_pk_fma_f32 v[108:109], v[132:133], v[108:109], v[154:155]
	s_waitcnt vmcnt(2)
	v_pk_fma_f32 v[106:107], v[130:131], v[106:107], v[172:173]
	v_pk_fma_f32 v[104:105], v[128:129], v[104:105], v[170:171]
	s_waitcnt vmcnt(1)
	v_pk_fma_f32 v[102:103], v[142:143], v[102:103], v[182:183]
	v_pk_fma_f32 v[100:101], v[140:141], v[100:101], v[180:181]
	s_waitcnt vmcnt(0)
	v_pk_fma_f32 v[98:99], v[138:139], v[98:99], v[190:191]
	v_pk_fma_f32 v[96:97], v[136:137], v[96:97], v[188:189]
	v_add_u32_e32 v170, 48, v178
	global_load_dwordx4 v[154:157], v[192:193], off nt
	global_load_dwordx4 v[172:175], v[192:193], off offset:64 nt
	global_load_dwordx4 v[180:183], v[192:193], off offset:512 nt
	global_load_dwordx4 v[188:191], v[192:193], off offset:576 nt
	ds_read_b32 v158, v160 offset:4224
	v_ashrrev_i32_e32 v171, 31, v170
	v_lshlrev_b64 v[192:193], 12, v[170:171]
	v_lshl_add_u64 v[192:193], s[48:49], 0, v[192:193]
	v_lshl_add_u64 v[192:193], v[192:193], 0, v[146:147]
	s_waitcnt lgkmcnt(0)
	v_pk_mul_f32 v[92:93], v[92:93], v[158:159] op_sel_hi:[1,0]
	v_pk_mul_f32 v[94:95], v[94:95], v[158:159] op_sel_hi:[1,0]
	v_pk_mul_f32 v[88:89], v[88:89], v[158:159] op_sel_hi:[1,0]
	v_pk_mul_f32 v[90:91], v[90:91], v[158:159] op_sel_hi:[1,0]
	v_pk_mul_f32 v[84:85], v[84:85], v[158:159] op_sel_hi:[1,0]
	v_pk_mul_f32 v[86:87], v[86:87], v[158:159] op_sel_hi:[1,0]
	v_pk_mul_f32 v[80:81], v[80:81], v[158:159] op_sel_hi:[1,0]
	v_pk_mul_f32 v[82:83], v[82:83], v[158:159] op_sel_hi:[1,0]
	s_waitcnt vmcnt(3)
	v_pk_fma_f32 v[94:95], v[134:135], v[94:95], v[156:157]
	v_pk_fma_f32 v[92:93], v[132:133], v[92:93], v[154:155]
	s_waitcnt vmcnt(2)
	v_pk_fma_f32 v[90:91], v[130:131], v[90:91], v[174:175]
	v_pk_fma_f32 v[88:89], v[128:129], v[88:89], v[172:173]
	s_waitcnt vmcnt(1)
	v_pk_fma_f32 v[86:87], v[142:143], v[86:87], v[182:183]
	v_pk_fma_f32 v[84:85], v[140:141], v[84:85], v[180:181]
	s_waitcnt vmcnt(0)
	v_pk_fma_f32 v[82:83], v[138:139], v[82:83], v[190:191]
	v_pk_fma_f32 v[80:81], v[136:137], v[80:81], v[188:189]
	v_add_u32_e32 v172, 0x80, v178
	global_load_dwordx4 v[154:157], v[192:193], off nt
	global_load_dwordx4 v[180:183], v[192:193], off offset:64 nt
	global_load_dwordx4 v[188:191], v[192:193], off offset:512 nt
	global_load_dwordx4 v[196:199], v[192:193], off offset:576 nt
	ds_read_b32 v158, v160 offset:4288
	v_ashrrev_i32_e32 v173, 31, v172
	v_lshlrev_b64 v[174:175], 12, v[172:173]
	v_lshl_add_u64 v[174:175], s[48:49], 0, v[174:175]
	v_lshl_add_u64 v[174:175], v[174:175], 0, v[146:147]
	s_waitcnt lgkmcnt(0)
	v_pk_mul_f32 v[76:77], v[76:77], v[158:159] op_sel_hi:[1,0]
	v_pk_mul_f32 v[78:79], v[78:79], v[158:159] op_sel_hi:[1,0]
	v_pk_mul_f32 v[72:73], v[72:73], v[158:159] op_sel_hi:[1,0]
	v_pk_mul_f32 v[74:75], v[74:75], v[158:159] op_sel_hi:[1,0]
	v_pk_mul_f32 v[68:69], v[68:69], v[158:159] op_sel_hi:[1,0]
	v_pk_mul_f32 v[70:71], v[70:71], v[158:159] op_sel_hi:[1,0]
	v_pk_mul_f32 v[64:65], v[64:65], v[158:159] op_sel_hi:[1,0]
	v_pk_mul_f32 v[66:67], v[66:67], v[158:159] op_sel_hi:[1,0]
	s_waitcnt vmcnt(3)
	v_pk_fma_f32 v[78:79], v[134:135], v[78:79], v[156:157]
	v_pk_fma_f32 v[76:77], v[132:133], v[76:77], v[154:155]
	s_waitcnt vmcnt(2)
	v_pk_fma_f32 v[74:75], v[130:131], v[74:75], v[182:183]
	v_pk_fma_f32 v[72:73], v[128:129], v[72:73], v[180:181]
	s_waitcnt vmcnt(1)
	v_pk_fma_f32 v[70:71], v[142:143], v[70:71], v[190:191]
	v_pk_fma_f32 v[68:69], v[140:141], v[68:69], v[188:189]
	s_waitcnt vmcnt(0)
	v_pk_fma_f32 v[66:67], v[138:139], v[66:67], v[198:199]
	v_pk_fma_f32 v[64:65], v[136:137], v[64:65], v[196:197]
	s_nop 0
	global_load_dwordx4 v[154:157], v[174:175], off nt
	global_load_dwordx4 v[180:183], v[174:175], off offset:64 nt
	global_load_dwordx4 v[188:191], v[174:175], off offset:512 nt
	global_load_dwordx4 v[196:199], v[174:175], off offset:576 nt
	ds_read_b32 v158, v160 offset:4608
	v_add_u32_e32 v174, 0x90, v178
	v_ashrrev_i32_e32 v175, 31, v174
	v_lshlrev_b64 v[192:193], 12, v[174:175]
	v_lshl_add_u64 v[192:193], s[48:49], 0, v[192:193]
	s_waitcnt lgkmcnt(0)
	v_pk_mul_f32 v[60:61], v[60:61], v[158:159] op_sel_hi:[1,0]
	v_pk_mul_f32 v[62:63], v[62:63], v[158:159] op_sel_hi:[1,0]
	v_pk_mul_f32 v[56:57], v[56:57], v[158:159] op_sel_hi:[1,0]
	v_pk_mul_f32 v[58:59], v[58:59], v[158:159] op_sel_hi:[1,0]
	v_pk_mul_f32 v[52:53], v[52:53], v[158:159] op_sel_hi:[1,0]
	v_pk_mul_f32 v[54:55], v[54:55], v[158:159] op_sel_hi:[1,0]
	v_pk_mul_f32 v[48:49], v[48:49], v[158:159] op_sel_hi:[1,0]
	v_pk_mul_f32 v[50:51], v[50:51], v[158:159] op_sel_hi:[1,0]
	v_lshl_add_u64 v[192:193], v[192:193], 0, v[146:147]
	s_waitcnt vmcnt(3)
	v_pk_fma_f32 v[62:63], v[134:135], v[62:63], v[156:157]
	v_pk_fma_f32 v[60:61], v[132:133], v[60:61], v[154:155]
	s_waitcnt vmcnt(2)
	v_pk_fma_f32 v[58:59], v[130:131], v[58:59], v[182:183]
	v_pk_fma_f32 v[56:57], v[128:129], v[56:57], v[180:181]
	s_waitcnt vmcnt(1)
	v_pk_fma_f32 v[54:55], v[142:143], v[54:55], v[190:191]
	v_pk_fma_f32 v[52:53], v[140:141], v[52:53], v[188:189]
	s_waitcnt vmcnt(0)
;     __device__ __forceinline__ void run(const f32x4 (&v)[2][2][4][2], const Unit& u, int wr, int wc, int fr, int fq, PG8_LAS unsigned char* lds, int wid, int lane) const {
;     ...
; #pragma unroll
;         for (int ai = 0; ai < 2; ++ai)
; #pragma unroll
;             for (int m = 0; m < 4; ++m) {
;                 float s = 0.f;
; #pragma unroll
;                 for (int bj = 0; bj < 2; ++bj)
; #pragma unroll
;                     for (int n = 0; n < 2; ++n) { const f32x4 x = v[ai][bj][m][n]; s += (x[0] * x[0] + x[1] * x[1]) + (x[2] * x[2] + x[3] * x[3]); }
;                 s += __shfl_xor(s, 16); s += __shfl_xor(s, 32);
;                 if (fq == 0) P[(ai * HALF + wr * 64 + m * 16 + fr) * 4 + wc] = s;
;     __device__ __forceinline__ void fused(f32x4 (&acc)[2][2][4][2], const Unit& u, int wr, int wc, int fr, int fq, PG8_LAS unsigned char* lds, int wid, int lane) const {
;     ...
;             for (int ai = 0; ai < 2; ++ai)
; #pragma unroll
;                 for (int m = 0; m < 4; ++m) { const int r = ai * HALF + wr * 64 + m * 16 + fr; const float rs = S[r]; const size_t off = (size_t)(row_off + u.pm * BM + r) * DM + col0;
; #pragma unroll
;                     for (int bj = 0; bj < 2; ++bj)
; #pragma unroll
;                         for (int n = 0; n < 2; ++n) { const f32x4 bs = __builtin_nontemporal_load((const f32x4*)(base + off + bj * HALF + n * 16)); acc[ai][bj][m][n] = bs + acc[ai][bj][m][n] * rs * g[bj][n]; }
;                     asm volatile("" : "+v"(acc[ai][0][m][0]), "+v"(acc[ai][0][m][1]), "+v"(acc[ai][1][m][0]), "+v"(acc[ai][1][m][1]));
;                     if (m & 1) asm volatile("" ::: "memory"); }
	v_pk_fma_f32 v[50:51], v[138:139], v[50:51], v[198:199]
	v_pk_fma_f32 v[48:49], v[136:137], v[48:49], v[196:197]
	v_add_u32_e32 v180, 0xa0, v178
	global_load_dwordx4 v[154:157], v[192:193], off nt
	global_load_dwordx4 v[188:191], v[192:193], off offset:64 nt
	global_load_dwordx4 v[196:199], v[192:193], off offset:512 nt
	global_load_dwordx4 v[200:203], v[192:193], off offset:576 nt
	ds_read_b32 v158, v160 offset:4672
	v_ashrrev_i32_e32 v181, 31, v180
	v_lshlrev_b64 v[182:183], 12, v[180:181]
	v_lshl_add_u64 v[182:183], s[48:49], 0, v[182:183]
	v_lshl_add_u64 v[182:183], v[182:183], 0, v[146:147]
	s_waitcnt lgkmcnt(0)
	v_pk_mul_f32 v[44:45], v[44:45], v[158:159] op_sel_hi:[1,0]
	v_pk_mul_f32 v[46:47], v[46:47], v[158:159] op_sel_hi:[1,0]
	v_pk_mul_f32 v[40:41], v[40:41], v[158:159] op_sel_hi:[1,0]
	v_pk_mul_f32 v[42:43], v[42:43], v[158:159] op_sel_hi:[1,0]
	v_pk_mul_f32 v[36:37], v[36:37], v[158:159] op_sel_hi:[1,0]
	v_pk_mul_f32 v[38:39], v[38:39], v[158:159] op_sel_hi:[1,0]
	v_pk_mul_f32 v[32:33], v[32:33], v[158:159] op_sel_hi:[1,0]
	v_pk_mul_f32 v[34:35], v[34:35], v[158:159] op_sel_hi:[1,0]
	s_waitcnt vmcnt(3)
	v_pk_fma_f32 v[46:47], v[134:135], v[46:47], v[156:157]
	v_pk_fma_f32 v[44:45], v[132:133], v[44:45], v[154:155]
	s_waitcnt vmcnt(2)
	v_pk_fma_f32 v[42:43], v[130:131], v[42:43], v[190:191]
	v_pk_fma_f32 v[40:41], v[128:129], v[40:41], v[188:189]
	s_waitcnt vmcnt(1)
	v_pk_fma_f32 v[38:39], v[142:143], v[38:39], v[198:199]
	v_pk_fma_f32 v[36:37], v[140:141], v[36:37], v[196:197]
	s_waitcnt vmcnt(0)
	v_pk_fma_f32 v[34:35], v[138:139], v[34:35], v[202:203]
	v_pk_fma_f32 v[32:33], v[136:137], v[32:33], v[200:201]
	s_nop 0
	global_load_dwordx4 v[154:157], v[182:183], off nt
	global_load_dwordx4 v[188:191], v[182:183], off offset:64 nt
	global_load_dwordx4 v[196:199], v[182:183], off offset:512 nt
	global_load_dwordx4 v[200:203], v[182:183], off offset:576 nt
	ds_read_b32 v158, v160 offset:4736
	v_add_u32_e32 v182, 0xb0, v178
	v_ashrrev_i32_e32 v183, 31, v182
	v_lshlrev_b64 v[192:193], 12, v[182:183]
	v_lshl_add_u64 v[192:193], s[48:49], 0, v[192:193]
	s_waitcnt lgkmcnt(0)
	v_pk_mul_f32 v[28:29], v[28:29], v[158:159] op_sel_hi:[1,0]
	v_pk_mul_f32 v[30:31], v[30:31], v[158:159] op_sel_hi:[1,0]
	v_pk_mul_f32 v[24:25], v[24:25], v[158:159] op_sel_hi:[1,0]
	v_pk_mul_f32 v[26:27], v[26:27], v[158:159] op_sel_hi:[1,0]
	v_pk_mul_f32 v[20:21], v[20:21], v[158:159] op_sel_hi:[1,0]
	v_pk_mul_f32 v[22:23], v[22:23], v[158:159] op_sel_hi:[1,0]
	v_pk_mul_f32 v[16:17], v[16:17], v[158:159] op_sel_hi:[1,0]
	v_pk_mul_f32 v[18:19], v[18:19], v[158:159] op_sel_hi:[1,0]
	v_lshl_add_u64 v[146:147], v[192:193], 0, v[146:147]
	v_mul_f32_e32 v158, v117, v117
	v_mul_f32_e32 v159, v119, v119
	v_mul_f32_e32 v192, v115, v115
	v_fmac_f32_e32 v158, v116, v116
	v_fmac_f32_e32 v159, v118, v118
	v_fmac_f32_e32 v192, v114, v114
	s_waitcnt vmcnt(3)
	v_pk_fma_f32 v[30:31], v[134:135], v[30:31], v[156:157]
	v_pk_fma_f32 v[28:29], v[132:133], v[28:29], v[154:155]
	s_waitcnt vmcnt(2)
	v_pk_fma_f32 v[26:27], v[130:131], v[26:27], v[190:191]
	v_pk_fma_f32 v[24:25], v[128:129], v[24:25], v[188:189]
	s_waitcnt vmcnt(1)
	v_pk_fma_f32 v[22:23], v[142:143], v[22:23], v[198:199]
	v_pk_fma_f32 v[20:21], v[140:141], v[20:21], v[196:197]
	s_waitcnt vmcnt(0)
	v_pk_fma_f32 v[18:19], v[138:139], v[18:19], v[202:203]
	v_pk_fma_f32 v[16:17], v[136:137], v[16:17], v[200:201]
	s_nop 0
	global_load_dwordx4 v[154:157], v[146:147], off nt
	global_load_dwordx4 v[188:191], v[146:147], off offset:64 nt
	global_load_dwordx4 v[196:199], v[146:147], off offset:512 nt
	global_load_dwordx4 v[200:203], v[146:147], off offset:576 nt
	v_mul_f32_e32 v146, v127, v127
	v_mul_f32_e32 v147, v121, v121
	v_fmac_f32_e32 v146, v126, v126
	v_fmac_f32_e32 v147, v120, v120
	v_add_f32_e32 v145, v145, v146
	v_add_f32_e32 v146, v147, v149
	v_add_f32_e32 v147, v158, v159
	v_add_f32_e32 v145, v145, v146
	v_add_f32_e32 v149, v187, v192
	v_add_f32_e32 v145, v147, v145
	v_add_f32_e32 v145, v149, v145
	ds_bpermute_b32 v146, v150, v145
	ds_read_b32 v158, v160 offset:4800
	s_waitcnt lgkmcnt(1)
	v_add_f32_e32 v145, v145, v146
	ds_bpermute_b32 v146, v151, v145
	s_waitcnt lgkmcnt(1)
	v_pk_mul_f32 v[12:13], v[12:13], v[158:159] op_sel_hi:[1,0]
	v_pk_mul_f32 v[14:15], v[14:15], v[158:159] op_sel_hi:[1,0]
	v_pk_mul_f32 v[8:9], v[8:9], v[158:159] op_sel_hi:[1,0]
	v_pk_mul_f32 v[10:11], v[10:11], v[158:159] op_sel_hi:[1,0]
	v_pk_mul_f32 v[4:5], v[4:5], v[158:159] op_sel_hi:[1,0]
	v_pk_mul_f32 v[6:7], v[6:7], v[158:159] op_sel_hi:[1,0]
	v_pk_mul_f32 v[0:1], v[0:1], v[158:159] op_sel_hi:[1,0]
	v_pk_mul_f32 v[2:3], v[2:3], v[158:159] op_sel_hi:[1,0]
	s_waitcnt vmcnt(3)
	v_pk_fma_f32 v[14:15], v[134:135], v[14:15], v[156:157]
	v_pk_fma_f32 v[12:13], v[132:133], v[12:13], v[154:155]
	s_waitcnt vmcnt(2)
	v_pk_fma_f32 v[10:11], v[130:131], v[10:11], v[190:191]
	v_pk_fma_f32 v[8:9], v[128:129], v[8:9], v[188:189]
	s_waitcnt vmcnt(1)
	v_pk_fma_f32 v[6:7], v[142:143], v[6:7], v[198:199]
	v_pk_fma_f32 v[4:5], v[140:141], v[4:5], v[196:197]
	s_waitcnt vmcnt(0)
	v_pk_fma_f32 v[2:3], v[138:139], v[2:3], v[202:203]
	v_pk_fma_f32 v[0:1], v[136:137], v[0:1], v[200:201]
	s_nop 0
	s_and_saveexec_b64 s[48:49], s[6:7]
	s_cbranch_execz .LBB0_792
	s_lshl_b32 s18, s68, 10
	s_add_i32 s18, s58, s18
	v_lshl_add_u32 v128, v148, 4, s18
	s_waitcnt lgkmcnt(0)
	v_add_f32_e32 v129, v145, v146
	ds_write_b32 v128, v129

;     __device__ __forceinline__ void run(const f32x4 (&v)[2][2][4][2], const Unit& u, int wr, int wc, int fr, int fq, PG8_LAS unsigned char* lds, int wid, int lane) const {
;     ...
;         const int row = wid * 32 + (lane & 31);
;         if (lane < 32) {
;             const float tot = (P[row * 4 + 0] + P[row * 4 + 1]) + (P[row * 4 + 2] + P[row * 4 + 3]);
;             __hip_atomic_store(xbuf + ((size_t)(pmg * BM + row) * 4 + u.pn), tot, __ATOMIC_RELAXED, __HIP_MEMORY_SCOPE_AGENT);
;         }
;         asm volatile("s_waitcnt vmcnt(0)" ::: "memory");
;         if (lane == 0) __hip_atomic_fetch_add(cnt + 64 * pmg, 1u, __ATOMIC_RELAXED, __HIP_MEMORY_SCOPE_AGENT);
;         if (wid == 0) {
;             unsigned sp = 0;
;             while ((unsigned)__builtin_amdgcn_readfirstlane(__hip_atomic_load(cnt + 64 * pmg, __ATOMIC_RELAXED, __HIP_MEMORY_SCOPE_AGENT)) < 32u) { __builtin_amdgcn_s_sleep(2); if (++sp > (1u << 22)) break; }
;             __builtin_amdgcn_fence(__ATOMIC_ACQUIRE, "agent");
;         }
;         asm volatile("s_waitcnt vmcnt(0) lgkmcnt(0)" ::: "memory"); __builtin_amdgcn_s_barrier(); asm volatile("" ::: "memory");
;         if (lane < 32) {
;             const float* slot = xbuf + (size_t)(pmg * BM + row) * 4; float t = 0.f;
; #pragma unroll
;             for (int k = 0; k < 4; ++k) t += __hip_atomic_load(slot + k, __ATOMIC_RELAXED, __HIP_MEMORY_SCOPE_AGENT);
;             S[row] = rsqrtf(t * (1.0f / 1024.0f) + eps);
.LBB0_808:
	s_or_b64 exec, exec, s[48:49]
	s_mov_b64 s[10:11], exec
	s_cmp_gt_u32 s36, 127
	s_cbranch_scc1 .LBB0_735
	s_lshl_b32 s18, s59, 8
	s_add_u32 s18, s18, s36
	v_add_u32_e32 v204, s18, v195
	v_ashrrev_i32_e32 v205, 31, v204
	v_lshl_add_u64 v[204:205], v[204:205], 4, s[6:7]
	v_add_u32_e32 v206, s36, v195
	v_lshlrev_b32_e32 v206, 2, v206
	s_mov_b32 s18, 0x40000
.Lpss_b_poll:
	global_load_dwordx4 v[128:131], v[204:205], off sc1
	global_load_dwordx4 v[132:135], v[204:205], off offset:1024 sc1
	s_waitcnt vmcnt(0)
	v_min3_f32 v207, v128, v129, v130
	v_min3_f32 v207, v207, v131, v132
	v_min3_f32 v207, v207, v133, v134
	v_min_f32_e32 v207, v207, v135
	v_cmp_gt_f32_e32 vcc, 0, v207
	s_cbranch_vccz .Lpss_b_ok
	s_sub_u32 s18, s18, 1
	s_cmp_lg_u32 s18, 0
	s_cbranch_scc1 .Lpss_b_poll
.Lpss_b_ok:
	v_add_f32_e32 v128, 0, v128
	v_add_f32_e32 v128, v128, v129
	v_add_f32_e32 v128, v128, v130
	v_add_f32_e32 v128, v128, v131
	v_fmamk_f32 v128, v128, 0x3a800000, v184
	v_mul_f32_e32 v129, 0x4b800000, v128
	v_cmp_gt_f32_e32 vcc, s67, v128
	s_nop 1
	v_cndmask_b32_e32 v128, v128, v129, vcc
	v_rsq_f32_e32 v128, v128
	s_nop 0
	v_mul_f32_e32 v129, 0x45800000, v128
	v_cndmask_b32_e32 v128, v128, v129, vcc
	ds_write_b32 v206, v128 offset:4096
	v_add_f32_e32 v132, 0, v132
	v_add_f32_e32 v132, v132, v133
	v_add_f32_e32 v132, v132, v134
	v_add_f32_e32 v132, v132, v135
	v_fmamk_f32 v132, v132, 0x3a800000, v184
	v_mul_f32_e32 v133, 0x4b800000, v132
	v_cmp_gt_f32_e32 vcc, s67, v132
	s_nop 1
	v_cndmask_b32_e32 v132, v132, v133, vcc
	v_rsq_f32_e32 v132, v132
	s_nop 0
	v_mul_f32_e32 v133, 0x45800000, v132
	v_cndmask_b32_e32 v132, v132, v133, vcc
	ds_write_b32 v206, v132 offset:4352
	s_branch .LBB0_735

; #define PG8_LAS __attribute__((address_space(3)))
;     __device__ __forceinline__ void run(const f32x4 (&v)[2][2][4][2], const Unit& u, int wr, int wc, int fr, int fq, PG8_LAS unsigned char* lds, int wid, int lane) const {
;     ...
;         if (wid == 0) {
;             unsigned sp = 0;
;             while ((unsigned)__builtin_amdgcn_readfirstlane(__hip_atomic_load(cnt + 64 * pmg, __ATOMIC_RELAXED, __HIP_MEMORY_SCOPE_AGENT)) < 32u) { __builtin_amdgcn_s_sleep(2); if (++sp > (1u << 22)) break; }
;             __builtin_amdgcn_fence(__ATOMIC_ACQUIRE, "agent");
;         }
;         asm volatile("s_waitcnt vmcnt(0) lgkmcnt(0)" ::: "memory"); __builtin_amdgcn_s_barrier(); asm volatile("" ::: "memory");
;         if (lane < 32) {
;             const float* slot = xbuf + (size_t)(pmg * BM + row) * 4; float t = 0.f;
; #pragma unroll
;             for (int k = 0; k < 4; ++k) t += __hip_atomic_load(slot + k, __ATOMIC_RELAXED, __HIP_MEMORY_SCOPE_AGENT);
;             S[row] = rsqrtf(t * (1.0f / 1024.0f) + eps);
;     __device__ __forceinline__ void fused(f32x4 (&acc)[2][2][4][2], const Unit& u, int wr, int wc, int fr, int fq, PG8_LAS unsigned char* lds, int wid, int lane) const {
;         const PG8_LAS float* S = (const PG8_LAS float*)(lds + 4096);
;         const int col0 = u.pn * BM + wc * 32 + 4 * fq;
;         st.run(acc, u, wr, wc, fr, fq, lds, wid, lane);
;         f32x4 g[2][2];
; #pragma unroll
;         for (int bj = 0; bj < 2; ++bj)
; #pragma unroll
;             for (int n = 0; n < 2; ++n) g[bj][n] = *(const f32x4*)(gv + col0 + bj * HALF + n * 16);
; #pragma unroll
;         for (int ai = 0; ai < 2; ++ai)
; #pragma unroll
;             for (int m = 0; m < 4; ++m) { const int r = ai * HALF + wr * 64 + m * 16 + fr; const float rs = S[r]; const size_t off = (size_t)(row_off + u.pm * BM + r) * DM + col0;
; #pragma unroll
;                 for (int bj = 0; bj < 2; ++bj)
; #pragma unroll
;                     for (int n = 0; n < 2; ++n) { const f32x4 bs = *(const f32x4*)(base + off + bj * HALF + n * 16); __builtin_nontemporal_store(bs + acc[ai][bj][m][n] * rs * g[bj][n], (f32x4*)(out + off + bj * HALF + n * 16)); }
.LBB0_1157:
	s_or_b64 exec, exec, s[10:11]
	s_lshl_b32 s78, s16, 5
	s_lshl_b32 s79, s24, 8
	s_or_b32 s78, s79, s78
	v_lshrrev_b32_e32 v137, 2, v138
	v_and_or_b32 v137, v137, 12, s78
	v_lshlrev_b32_e32 v137, 2, v137
	v_and_b32_e32 v190, 8, v157
	v_sub_u32_e32 v136, v157, v190
	v_lshlrev_b32_e32 v190, 3, v190
	v_lshl_add_u32 v136, v136, 12, v137
	v_add_u32_e32 v136, v136, v190
	s_lshl_b32 s78, s50, 12
	s_add_i32 s78, s51, s78
	s_ashr_i32 s79, s78, 31
	s_lshl_b64 s[78:79], s[78:79], 2
	s_add_u32 s78, s14, s78
	s_addc_u32 s79, s15, s79
	s_add_u32 s78, s78, s22
	s_addc_u32 s79, s79, s23
	v_add_u32_e32 v191, v137, v190
	global_load_dwordx4 v[244:247], v191, s[78:79]
	global_load_dwordx4 v[248:251], v191, s[78:79] offset:512
	s_lshl_b32 s78, s50, 14
	s_lshl_b32 s76, s53, 8
	s_add_i32 s76, s76, s78
	s_mov_b32 s77, 0
	s_lshl_b64 s[76:77], s[76:77], 12
	s_add_u32 s76, s12, s76
	s_addc_u32 s77, s13, s77
	v_mov_b32_e32 v192, v136
	v_add_u32_e32 v193, 0x8000, v136
	global_load_dwordx4 v[158:161], v192, s[76:77] nt
	global_load_dwordx4 v[162:165], v193, s[76:77] nt
	v_mov_b32_e32 v192, v136
	v_add_u32_e32 v193, 0x8000, v136
	global_load_dwordx4 v[166:169], v192, s[76:77] offset:512 nt
	global_load_dwordx4 v[170:173], v193, s[76:77] offset:512 nt
	v_add_u32_e32 v192, 0x10000, v136
	v_add_u32_e32 v193, 0x18000, v136
	global_load_dwordx4 v[174:177], v192, s[76:77] nt
	global_load_dwordx4 v[178:181], v193, s[76:77] nt
	v_add_u32_e32 v192, 0x10000, v136
	v_add_u32_e32 v193, 0x18000, v136
	global_load_dwordx4 v[182:185], v192, s[76:77] offset:512 nt
	global_load_dwordx4 v[186:189], v193, s[76:77] offset:512 nt
	v_add_u32_e32 v192, 0x20000, v136
	v_add_u32_e32 v193, 0x28000, v136
	global_load_dwordx4 v[196:199], v192, s[76:77] nt
	global_load_dwordx4 v[200:203], v193, s[76:77] nt
	v_add_u32_e32 v192, 0x20000, v136
	v_add_u32_e32 v193, 0x28000, v136
	global_load_dwordx4 v[204:207], v192, s[76:77] offset:512 nt
	global_load_dwordx4 v[208:211], v193, s[76:77] offset:512 nt
	v_add_u32_e32 v192, 0x30000, v136
	v_add_u32_e32 v193, 0x38000, v136
	global_load_dwordx4 v[212:215], v192, s[76:77] nt
	global_load_dwordx4 v[216:219], v193, s[76:77] nt
	v_add_u32_e32 v192, 0x30000, v136
	v_add_u32_e32 v193, 0x38000, v136
	global_load_dwordx4 v[220:223], v192, s[76:77] offset:512 nt
	global_load_dwordx4 v[224:227], v193, s[76:77] offset:512 nt
	s_mov_b64 s[10:11], exec
	s_cmp_gt_u32 s52, 127
	s_cbranch_scc1 .LBB0_1113
	s_lshl_b32 s25, s28, 8
	s_add_u32 s25, s25, s52
	v_add_u32_e32 v136, s25, v195
	v_ashrrev_i32_e32 v137, 31, v136
	v_lshl_add_u64 v[136:137], v[136:137], 4, s[8:9]
	v_add_u32_e32 v190, s52, v195
	v_lshlrev_b32_e32 v190, 2, v190
	s_mov_b32 s25, 0x40000
.Lpss_c_poll:
	global_load_dwordx4 v[128:131], v[136:137], off sc1
	global_load_dwordx4 v[132:135], v[136:137], off offset:1024 sc1
	s_waitcnt vmcnt(0)
	v_min3_f32 v191, v128, v129, v130
	v_min3_f32 v191, v191, v131, v132
	v_min3_f32 v191, v191, v133, v134
	v_min_f32_e32 v191, v191, v135
	v_cmp_gt_f32_e32 vcc, 0, v191
	s_cbranch_vccz .Lpss_c_ok
	s_sub_u32 s25, s25, 1
	s_cmp_lg_u32 s25, 0
	s_cbranch_scc1 .Lpss_c_poll
.Lpss_c_ok:
	v_add_f32_e32 v128, 0, v128
	v_add_f32_e32 v128, v128, v129
	v_add_f32_e32 v128, v128, v130
	v_add_f32_e32 v128, v128, v131
	v_fmamk_f32 v128, v128, 0x3a800000, v154
	v_mul_f32_e32 v129, 0x4b800000, v128
	v_cmp_gt_f32_e32 vcc, s48, v128
	s_nop 1
	v_cndmask_b32_e32 v128, v128, v129, vcc
	v_rsq_f32_e32 v128, v128
	s_nop 0
	v_mul_f32_e32 v129, 0x45800000, v128
	v_cndmask_b32_e32 v128, v128, v129, vcc
	ds_write_b32 v190, v128 offset:4096
	v_add_f32_e32 v132, 0, v132
	v_add_f32_e32 v132, v132, v133
	v_add_f32_e32 v132, v132, v134
	v_add_f32_e32 v132, v132, v135
	v_fmamk_f32 v132, v132, 0x3a800000, v154
	v_mul_f32_e32 v133, 0x4b800000, v132
	v_cmp_gt_f32_e32 vcc, s48, v132
	s_nop 1
	v_cndmask_b32_e32 v132, v132, v133, vcc
	v_rsq_f32_e32 v132, v132
	s_nop 0
	v_mul_f32_e32 v133, 0x45800000, v132
	v_cndmask_b32_e32 v132, v132, v133, vcc
	ds_write_b32 v190, v132 offset:4352
	s_branch .LBB0_1113
